# sharded grid barrier + redistribute sample-row out-proj tiles and gate tiles over idle workgroups
# speedup vs baseline: 1.0327x; 1.0196x over previous
; __device__ __forceinline__ void xcd_barrier(const XB& b) {
;     ...
;         __builtin_amdgcn_fence(__ATOMIC_ACQUIRE, "agent");
;         asm volatile("s_waitcnt vmcnt(0)" ::: "memory");
; __global__ void __launch_bounds__(512, 2) hymba_fwd(Params p) {
;     ...
;     grid.sync();
.Lgs_inv:
	s_waitcnt vmcnt(0)
	buffer_inv sc1
	s_waitcnt vmcnt(0)

; __device__ __forceinline__ f32x4 mfma16(h16x8 a, h16x8 b, f32x4 c) { return __builtin_amdgcn_mfma_f32_16x16x32_f16(a, b, c, 0, 0, 0); }
; template <int MODE>
; __device__ __forceinline__ void skinny(const Params& p, const h16* A, int lda, int row0, int nrt, const h16* Bt, int K, int nct) {
;     const int lane = threadIdx.x & 63, wave = threadIdx.x >> 6, fr = lane & 15, fq = lane >> 4;
;     const int gw = blockIdx.x * 8 + wave, ngw = gridDim.x * 8;
;     unsigned char* ws = p.ws;
;     for (int task = gw; task < nrt * nct; task += ngw) {
;         const int rt = task % nrt, ct = task / nrt;
;         const h16* ap = A + (size_t)(row0 + rt * 16 + fr) * lda + fq * 8;
;         const h16* bp = Bt + (size_t)(ct * 16 + fr) * K + fq * 8;
;         f32x4 acc = {0.f, 0.f, 0.f, 0.f};
; #pragma unroll 8
;         for (int k = 0; k < K; k += 32) { const h16x8 a = *(const h16x8*)(ap + k); const h16x8 b = *(const h16x8*)(bp + k); acc = mfma16(b, a, acc); }
;         const int row = row0 + rt * 16 + fr, col = ct * 16 + fq * 4;
.LBB0_89:
	v_addc_co_u32_e64 v10, vcc, v131, v133, s[6:7]
	s_movk_i32 s0, 0x408
	v_bfe_u32 v144, v132, 4, 2
	v_and_b32_e32 v131, 15, v132
	s_lshl_b32 s88, s33, 3
	v_and_b32_e32 v56, 7, v130
	v_lshrrev_b32_e32 v57, 3, v130
	v_lshl_add_u32 v54, v57, 1, v56
	v_add_u32_e32 v54, 0x24c, v54
	v_add_u32_e32 v58, 0x3ea, v57
	v_cmp_eq_u32_e32 vcc, 2, v56
	v_cmp_gt_u32_e64 s[98:99], 30, v57
	s_and_b64 vcc, vcc, s[98:99]
	v_mov_b32_e32 v59, 0x7fff0000
	v_cndmask_b32_e32 v58, v59, v58, vcc
	v_cmp_gt_u32_e32 vcc, 2, v56
	s_nop 1
	v_cndmask_b32_e32 v54, v58, v54, vcc
	v_add_u32_e32 v55, 1, v54
	v_subrev_u32_e32 v58, 0xcf, v57
	v_mul_u32_u24_e32 v58, 12, v58
	v_add_u32_e32 v59, v58, v56
	v_add_u32_e32 v58, 12, v58
	v_cmp_lt_u32_e32 vcc, 0xce, v57
	s_nop 1
	v_cndmask_b32_e32 v54, v54, v59, vcc
	v_cndmask_b32_e32 v55, v55, v58, vcc
	v_min_u32_e32 v55, 0x408, v55
	v_mov_b32_e32 v56, 8
	s_cmpk_eq_i32 s33, 0x100
	s_cselect_b64 s[98:99], -1, 0
	v_mov_b32_e32 v58, 0x408
	v_mov_b32_e32 v59, s88
	v_cndmask_b32_e64 v54, v130, v54, s[98:99]
	v_cndmask_b32_e64 v55, v58, v55, s[98:99]
	v_cndmask_b32_e64 v56, v59, v56, s[98:99]
	v_cmp_lt_i32_e32 vcc, v54, v55
	v_lshlrev_b32_e32 v138, 2, v144
	v_lshlrev_b32_e32 v140, 4, v144
	s_and_saveexec_b64 s[0:1], vcc
	s_cbranch_execz .LBB0_94
	s_add_u32 s6, s82, 0x19c8000
	s_movk_i32 s24, 0xffe0
	s_movk_i32 s26, 0xffe4
	s_movk_i32 s28, 0xffe8
	s_movk_i32 s30, 0xffec
	s_addc_u32 s7, s83, 0
	v_mov_b32_e32 v141, 0
	s_mov_b64 s[8:9], 0
	s_mov_b32 s34, 0xfe03f81
	s_mov_b64 s[10:11], 0x200
	s_mov_b32 s25, -1
	s_mov_b32 s27, -1
	s_mov_b32 s29, -1
	s_mov_b32 s31, -1
	s_movk_i32 s35, 0x407
	v_mov_b32_e32 v11, v54

; __device__ __forceinline__ f32x4 mfma16(h16x8 a, h16x8 b, f32x4 c) { return __builtin_amdgcn_mfma_f32_16x16x32_f16(a, b, c, 0, 0, 0); }
; template <int MODE>
; __device__ __forceinline__ void skinny(const Params& p, const h16* A, int lda, int row0, int nrt, const h16* Bt, int K, int nct) {
;     ...
;     for (int task = gw; task < nrt * nct; task += ngw) {
;         const int rt = task % nrt, ct = task / nrt;
;         const h16* ap = A + (size_t)(row0 + rt * 16 + fr) * lda + fq * 8;
;         const h16* bp = Bt + (size_t)(ct * 16 + fr) * K + fq * 8;
;         f32x4 acc = {0.f, 0.f, 0.f, 0.f};
; #pragma unroll 8
;         for (int k = 0; k < K; k += 32) { const h16x8 a = *(const h16x8*)(ap + k); const h16x8 b = *(const h16x8*)(bp + k); acc = mfma16(b, a, acc); }
;         const int row = row0 + rt * 16 + fr, col = ct * 16 + fq * 4;
;         if (MODE == SK_GATES) {
;             const float* bi = p.in[12]; const float* bf = p.in[13];
;             f32x4 o;
; #pragma unroll
;             for (int r = 0; r < 4; ++r) { const int cc = col + r; o[r] = acc[r] + (cc < 8 ? bi[cc] : bf[cc - 8]); }
;             *(f32x4*)((float*)(ws + OFF_GATES) + (size_t)row * 16 + col) = o;
.LBB0_92:
	v_lshl_add_u64 v[14:15], v[6:7], 0, v[140:141]
	v_add_co_u32_e32 v50, vcc, 0x1b72000, v14
	v_lshl_add_u64 v[16:17], v[8:9], 0, v[140:141]
	s_nop 0
	v_addc_co_u32_e32 v51, vcc, 0, v15, vcc
	v_add_co_u32_e32 v52, vcc, 0x780000, v16
	s_addk_i32 s38, 0x100
	s_nop 0
	v_addc_co_u32_e32 v53, vcc, 0, v17, vcc
	global_load_dwordx4 v[14:17], v[50:51], off offset:2304
	global_load_dwordx4 v[18:21], v[50:51], off offset:2368
	global_load_dwordx4 v[22:25], v[50:51], off offset:2432
	global_load_dwordx4 v[26:29], v[50:51], off offset:2496
	global_load_dwordx4 v[30:33], v[50:51], off offset:2560
	global_load_dwordx4 v[34:37], v[52:53], off
	global_load_dwordx4 v[38:41], v[52:53], off offset:64
	global_load_dwordx4 v[42:45], v[52:53], off offset:128
	global_load_dwordx4 v[46:49], v[52:53], off offset:192
	v_lshl_add_u64 v[6:7], v[6:7], 0, s[10:11]
	s_cmpk_gt_u32 s38, 0x3df
	v_lshl_add_u64 v[8:9], v[8:9], 0, s[10:11]
	s_waitcnt vmcnt(0)
	v_mfma_f32_16x16x32_f16 v[0:3], v[34:37], v[14:17], v[0:3]
	global_load_dwordx4 v[14:17], v[52:53], off offset:256
	v_mfma_f32_16x16x32_f16 v[0:3], v[38:41], v[18:21], v[0:3]
	global_load_dwordx4 v[18:21], v[52:53], off offset:320
	v_mfma_f32_16x16x32_f16 v[0:3], v[42:45], v[22:25], v[0:3]
	global_load_dwordx4 v[22:25], v[50:51], off offset:2624
	v_mfma_f32_16x16x32_f16 v[0:3], v[46:49], v[26:29], v[0:3]
	global_load_dwordx4 v[26:29], v[52:53], off offset:384
	global_load_dwordx4 v[34:37], v[50:51], off offset:2688
	s_waitcnt vmcnt(0)
	v_mfma_f32_16x16x32_f16 v[0:3], v[14:17], v[30:33], v[0:3]
	global_load_dwordx4 v[14:17], v[52:53], off offset:448
	v_mfma_f32_16x16x32_f16 v[0:3], v[18:21], v[22:25], v[0:3]
	global_load_dwordx4 v[18:21], v[50:51], off offset:2752
	v_mfma_f32_16x16x32_f16 v[0:3], v[26:29], v[34:37], v[0:3]
	s_waitcnt vmcnt(0)
	v_mfma_f32_16x16x32_f16 v[0:3], v[14:17], v[18:21], v[0:3]
	s_cbranch_scc0 .LBB0_92
	v_or_b32_e32 v6, v12, v138
	v_ashrrev_i32_e32 v7, 31, v6
	v_lshlrev_b64 v[8:9], 2, v[6:7]
	v_mov_b32_e32 v7, v141
	v_lshl_add_u64 v[14:15], v[6:7], 2, s[18:19]
	v_lshl_add_u64 v[12:13], s[16:17], 0, v[8:9]
	v_lshl_add_u64 v[16:17], v[14:15], 0, s[24:25]
	v_cmp_gt_i32_e32 vcc, 8, v6
	v_or_b32_e32 v7, 1, v6
	v_lshl_add_u64 v[18:19], v[12:13], 0, 4
	v_cndmask_b32_e32 v17, v17, v13, vcc
	v_cndmask_b32_e32 v16, v16, v12, vcc
	v_lshl_add_u64 v[20:21], v[14:15], 0, s[26:27]
	v_cmp_gt_i32_e32 vcc, 8, v7
	v_or_b32_e32 v7, 2, v6
	global_load_dword v16, v[16:17], off
	v_cndmask_b32_e32 v19, v21, v19, vcc
	v_cndmask_b32_e32 v18, v20, v18, vcc
	v_lshl_add_u64 v[20:21], v[12:13], 0, 8
	v_lshl_add_u64 v[22:23], v[14:15], 0, s[28:29]
	v_cmp_gt_i32_e32 vcc, 8, v7
	v_or_b32_e32 v17, 3, v6
	v_lshl_add_u64 v[6:7], v[12:13], 0, 12
	v_cndmask_b32_e32 v21, v23, v21, vcc
	v_cndmask_b32_e32 v20, v22, v20, vcc
	v_lshl_add_u64 v[12:13], v[14:15], 0, s[30:31]
	v_cmp_gt_i32_e32 vcc, 8, v17
	global_load_dword v20, v[20:21], off
	v_lshlrev_b64 v[4:5], 6, v[4:5]
	v_cndmask_b32_e32 v7, v13, v7, vcc
	v_cndmask_b32_e32 v6, v12, v6, vcc
	global_load_dword v21, v[6:7], off
	global_load_dword v17, v[18:19], off
	v_add_u32_e32 v11, v56, v11
	v_lshl_add_u64 v[4:5], s[6:7], 0, v[4:5]
	v_cmp_le_i32_e32 vcc, v55, v11
	v_lshl_add_u64 v[4:5], v[4:5], 0, v[8:9]
	s_or_b64 s[8:9], vcc, s[8:9]
	s_waitcnt vmcnt(0)
	v_pk_add_f32 v[2:3], v[2:3], v[20:21]
	v_pk_add_f32 v[0:1], v[0:1], v[16:17]
	global_store_dwordx4 v[4:5], v[0:3], off
	s_andn2_b64 exec, exec, s[8:9]
	s_cbranch_execnz .LBB0_91

; __device__ __forceinline__ f32x4 mfma16(h16x8 a, h16x8 b, f32x4 c) { return __builtin_amdgcn_mfma_f32_16x16x32_f16(a, b, c, 0, 0, 0); }
; template <int MODE>
; __device__ __forceinline__ void skinny(const Params& p, const h16* A, int lda, int row0, int nrt, const h16* Bt, int K, int nct) {
;     ...
;     const int gw = blockIdx.x * 8 + wave, ngw = gridDim.x * 8;
;     unsigned char* ws = p.ws;
;     for (int task = gw; task < nrt * nct; task += ngw) {
;         const int rt = task % nrt, ct = task / nrt;
;         const h16* ap = A + (size_t)(row0 + rt * 16 + fr) * lda + fq * 8;
;         const h16* bp = Bt + (size_t)(ct * 16 + fr) * K + fq * 8;
;         f32x4 acc = {0.f, 0.f, 0.f, 0.f};
; #pragma unroll 8
;         for (int k = 0; k < K; k += 32) { const h16x8 a = *(const h16x8*)(ap + k); const h16x8 b = *(const h16x8*)(bp + k); acc = mfma16(b, a, acc); }
;         const int row = row0 + rt * 16 + fr, col = ct * 16 + fq * 4;
;         if (MODE == SK_GATES) {
;             const float* bi = p.in[12]; const float* bf = p.in[13];
;             f32x4 o;
; #pragma unroll
;             for (int r = 0; r < 4; ++r) { const int cc = col + r; o[r] = acc[r] + (cc < 8 ? bi[cc] : bf[cc - 8]); }
;             *(f32x4*)((float*)(ws + OFF_GATES) + (size_t)row * 16 + col) = o;
;         } else if (MODE == SK_OUT) {
;             const int s = row - MP;
;             f32x4 v = acc + *(const f32x4*)(p.in[1] + (size_t)s * D + col);
;             *(f32x4*)((float*)(ws + OFF_X1) + (size_t)row * D + col) = v;
;             *(h16x4*)((h16*)(ws + OFF_X116) + (size_t)row * D + col) = pack4(v);
;             float ss = v[0] * v[0] + v[1] * v[1] + v[2] * v[2] + v[3] * v[3];
;             ss += __shfl_xor(ss, 16); ss += __shfl_xor(ss, 32);
.LBB0_442:
	s_movk_i32 s0, 0x200
	v_or_b32_e32 v137, 0x4000, v131
	v_and_b32_e32 v16, 7, v130
	v_lshrrev_b32_e32 v17, 3, v130
	v_lshl_add_u32 v17, v17, 1, v16
	v_cmp_gt_u32_e32 vcc, 2, v16
	s_cmpk_eq_i32 s33, 0x100
	s_cselect_b64 s[98:99], -1, 0
	v_mov_b32_e32 v18, 0x7fff0000
	v_cndmask_b32_e32 v16, v18, v17, vcc
	v_cndmask_b32_e64 v16, v130, v16, s[98:99]
	v_cmp_gt_i32_e32 vcc, s0, v16
	s_and_saveexec_b64 s[0:1], vcc
	s_cbranch_execz .LBB0_449
	v_xor_b32_e32 v0, 16, v129
	v_cmp_lt_i32_e32 vcc, v0, v135
	v_mov_b32_e32 v5, 0
	v_cmp_eq_u32_e64 s[6:7], 0, v144
	v_cndmask_b32_e32 v0, v129, v0, vcc
	s_waitcnt vmcnt(2)
	v_lshlrev_b32_e32 v12, 2, v0
	v_xor_b32_e32 v0, 32, v129
	v_cmp_lt_i32_e32 vcc, v0, v135
	v_mov_b32_e32 v141, v5
	s_mov_b64 s[8:9], 0
	v_cndmask_b32_e32 v0, v129, v0, vcc
	v_lshlrev_b32_e32 v13, 2, v0
	s_mov_b64 s[12:13], 0x200
	s_movk_i32 s18, 0x1ff
	v_mov_b32_e32 v14, v16
	s_branch .LBB0_445
